# GEMM K-loops: mid-segment setprio 0/1 toggles removed (one priority window per MFMA segment)
# baseline (speedup 1.0000x reference)
; #define PG8_STAGE(bufoff, gbase, voff) do { _Pragma("unroll") for (int _i = 0; _i < 2; ++_i) \
;         __builtin_amdgcn_global_load_lds((const unsigned*)((const char*)(gbase) + (voff)[_i]), (PG8_LAS unsigned*)(lds + (bufoff) + ldsw + _i * 8192), 16, 0, 0); } while (0)
; #define PG8_LDA(dst, b, h) do { _Pragma("unroll") for (int m = 0; m < 4; ++m) _Pragma("unroll") for (int k = 0; k < 2; ++k) dst[m][k] = *(const PG8_LAS bf16x8*)(lds + PG8_SA(b, h) + aoff + m * 2048 + k * 1024); } while (0)
; #define PG8_LDB(dst, b, h) do { _Pragma("unroll") for (int n = 0; n < 2; ++n) _Pragma("unroll") for (int k = 0; k < 2; ++k) dst[n][k] = *(const PG8_LAS bf16x8*)(lds + PG8_SB(b, h) + boff + n * 2048 + k * 1024); } while (0)
; #define PG8_WAIT_V(n) asm volatile("s_waitcnt vmcnt(" #n ")" ::: "memory")
; #define PG8_WAIT_L(n) asm volatile("s_waitcnt lgkmcnt(" #n ")" ::: "memory")
; template <class Epi, class Sched, bool ALIGN_EPI = false, bool SP2 = false, bool UNIFORM_NT = false>
; __device__ __forceinline__ void gemm_phase(PG8_LAS unsigned char* lds, const Gemm g, const Sched& S, const Epi& E, int tid_in) {
;     ...
;         const bool has_next = S.next(ui + 1, nxt);
;         const char* nA = has_next ? (const char*)g.A + (size_t)nxt.pm * tstepA + (size_t)nxt.kofs * 2 : cA; const char* nB = has_next ? (const char*)g.Bt + (size_t)nxt.pn * tstepB + (size_t)nxt.kofs * 2 : cB;
;         const int nt = UNIFORM_NT ? nt_uniform : cur.nt;
;         for (int t = 0; t < nt; t += 2) {
;             const bool last = (t == nt - 2);
;             const char* a1 = cA + (size_t)(t + 1) * kstep;
;             const char* a2 = last ? nA : cA + (size_t)(t + 2) * kstep; const char* b2 = last ? nB : cB + (size_t)(t + 2) * kstep;
;             const char* a3 = a2 + kstep; const char* b3 = b2 + kstep;
;             if (last && has_next) S.a_ready(nxt);
;             if constexpr (SP2) {
;             PG8_LDB(B0, 0, 0); PG8_LDB(B1, 0, 1); PG8_SCHED; PG8_LDA(At, 0, 0); PG8_STAGE(PG8_SA(1, 1), a1 + hstepA, voffA);
;             PG8_WAIT_V(8); PG8_WAIT_L(0); PG8_BAR; PG8_MMA(0, 0, At, B0); PG8_MMA(0, 1, At, B1); PG8_BAR; PG8_SCHED;
;             PG8_LDA(At, 0, 1); PG8_STAGE(PG8_SB(0, 0), b2, voffB); PG8_STAGE(PG8_SB(0, 1), b2 + hstepB, voffB); PG8_STAGE(PG8_SA(0, 0), a2, voffA);
;             PG8_WAIT_V(8); PG8_WAIT_L(0); PG8_BAR; PG8_MMA(1, 0, At, B0); PG8_MMA(1, 1, At, B1); PG8_BAR; PG8_SCHED;
.LBB0_54:
	s_add_u32 s47, s54, 0xfffc0080
	s_addc_u32 s48, s55, -1
	s_add_i32 s49, 0, 0x10000
	s_cmp_eq_u32 s46, 12
	s_cselect_b32 s59, s12, s48
	s_cselect_b32 s58, s13, s47
	v_add_u32_e32 v140, s49, v143
	s_cselect_b32 s57, s31, s45
	s_cselect_b32 s56, s35, s43
	s_add_i32 s47, 0, 0x14000
	ds_read_b128 v[146:149], v140
	ds_read_b128 v[150:153], v140 offset:1024
	ds_read_b128 v[154:157], v140 offset:2048
	ds_read_b128 v[158:161], v140 offset:3072
	v_add_u32_e32 v140, s47, v143
	ds_read_b128 v[162:165], v140
	ds_read_b128 v[166:169], v140 offset:1024
	ds_read_b128 v[170:173], v140 offset:2048
	ds_read_b128 v[174:177], v140 offset:3072
	v_lshl_add_u64 v[140:141], s[54:55], 0, v[136:137]
	s_add_i32 m0, s7, 0xc000
	ds_read_b128 v[178:181], v145
	ds_read_b128 v[182:185], v145 offset:1024
	ds_read_b128 v[186:189], v145 offset:2048
	ds_read_b128 v[190:193], v145 offset:3072
	ds_read_b128 v[194:197], v145 offset:4096
	ds_read_b128 v[198:201], v145 offset:5120
	ds_read_b128 v[202:205], v145 offset:6144
	ds_read_b128 v[206:209], v145 offset:7168
	global_load_lds_dwordx4 v[140:141], off
	v_lshl_add_u64 v[140:141], s[54:55], 0, v[138:139]
	s_add_i32 m0, s7, 0xe000
	s_nop 0
	global_load_lds_dwordx4 v[140:141], off
	s_waitcnt vmcnt(8)
	s_waitcnt lgkmcnt(0)
	s_barrier
	s_setprio 1
	s_waitcnt lgkmcnt(0)
	v_mfma_f32_16x16x32_bf16 v[126:129], v[146:149], v[178:181], v[126:129]
	v_mfma_f32_16x16x32_bf16 v[122:125], v[154:157], v[178:181], v[122:125]
	v_mfma_f32_16x16x32_bf16 v[110:113], v[146:149], v[186:189], v[110:113]
	v_mfma_f32_16x16x32_bf16 v[106:109], v[154:157], v[186:189], v[106:109]
	v_mfma_f32_16x16x32_bf16 v[94:97], v[146:149], v[194:197], v[94:97]
	v_mfma_f32_16x16x32_bf16 v[90:93], v[154:157], v[194:197], v[90:93]
	v_mfma_f32_16x16x32_bf16 v[78:81], v[146:149], v[202:205], v[78:81]
	v_mfma_f32_16x16x32_bf16 v[74:77], v[154:157], v[202:205], v[74:77]
	v_mfma_f32_16x16x32_bf16 v[126:129], v[150:153], v[182:185], v[126:129]
	v_mfma_f32_16x16x32_bf16 v[122:125], v[158:161], v[182:185], v[122:125]
	v_mfma_f32_16x16x32_bf16 v[110:113], v[150:153], v[190:193], v[110:113]
	v_mfma_f32_16x16x32_bf16 v[106:109], v[158:161], v[190:193], v[106:109]
	v_mfma_f32_16x16x32_bf16 v[94:97], v[150:153], v[198:201], v[94:97]
	v_mfma_f32_16x16x32_bf16 v[90:93], v[158:161], v[198:201], v[90:93]
	v_mfma_f32_16x16x32_bf16 v[78:81], v[150:153], v[206:209], v[78:81]
	v_mfma_f32_16x16x32_bf16 v[74:77], v[158:161], v[206:209], v[74:77]
	v_mfma_f32_16x16x32_bf16 v[118:121], v[162:165], v[178:181], v[118:121]
	v_mfma_f32_16x16x32_bf16 v[114:117], v[170:173], v[178:181], v[114:117]
	v_mfma_f32_16x16x32_bf16 v[102:105], v[162:165], v[186:189], v[102:105]
	v_mfma_f32_16x16x32_bf16 v[98:101], v[170:173], v[186:189], v[98:101]
	v_mfma_f32_16x16x32_bf16 v[86:89], v[162:165], v[194:197], v[86:89]
	v_mfma_f32_16x16x32_bf16 v[82:85], v[170:173], v[194:197], v[82:85]
	v_mfma_f32_16x16x32_bf16 v[70:73], v[162:165], v[202:205], v[70:73]
	v_mfma_f32_16x16x32_bf16 v[66:69], v[170:173], v[202:205], v[66:69]
	v_mfma_f32_16x16x32_bf16 v[118:121], v[166:169], v[182:185], v[118:121]
	v_mfma_f32_16x16x32_bf16 v[114:117], v[174:177], v[182:185], v[114:117]
	v_mfma_f32_16x16x32_bf16 v[102:105], v[166:169], v[190:193], v[102:105]
	v_mfma_f32_16x16x32_bf16 v[98:101], v[174:177], v[190:193], v[98:101]
	v_mfma_f32_16x16x32_bf16 v[86:89], v[166:169], v[198:201], v[86:89]
	v_mfma_f32_16x16x32_bf16 v[82:85], v[174:177], v[198:201], v[82:85]
	v_mfma_f32_16x16x32_bf16 v[70:73], v[166:169], v[206:209], v[70:73]
	v_mfma_f32_16x16x32_bf16 v[66:69], v[174:177], v[206:209], v[66:69]
	s_setprio 0
	s_barrier
	s_add_i32 s48, s49, s0
	v_lshl_add_u64 v[140:141], s[56:57], 0, v[0:1]
	s_mov_b32 m0, s48
	ds_read_b128 v[178:181], v145 offset:16384
	ds_read_b128 v[182:185], v145 offset:17408
	ds_read_b128 v[186:189], v145 offset:18432
	ds_read_b128 v[190:193], v145 offset:19456
	ds_read_b128 v[194:197], v145 offset:20480
	ds_read_b128 v[198:201], v145 offset:21504
	ds_read_b128 v[202:205], v145 offset:22528
	ds_read_b128 v[206:209], v145 offset:23552
	global_load_lds_dwordx4 v[140:141], off
	s_add_i32 m0, s48, 0x2000
	s_add_u32 s48, s56, 0x40000
	v_lshl_add_u64 v[210:211], s[56:57], 0, v[130:131]
	s_addc_u32 s49, s57, 0
	s_add_i32 s47, s47, s0
	global_load_lds_dwordx4 v[210:211], off
	v_lshl_add_u64 v[212:213], s[48:49], 0, v[0:1]
	s_mov_b32 m0, s47
	v_lshl_add_u64 v[214:215], s[58:59], 0, v[132:133]
	global_load_lds_dwordx4 v[212:213], off
	v_lshl_add_u64 v[212:213], s[48:49], 0, v[130:131]
	s_add_i32 m0, s47, 0x2000
	s_nop 0
	global_load_lds_dwordx4 v[212:213], off
	v_lshl_add_u64 v[212:213], s[58:59], 0, v[134:135]
	s_mov_b32 m0, s7
	s_nop 0
	global_load_lds_dwordx4 v[212:213], off
	s_mov_b32 m0, s8
	s_nop 0
	global_load_lds_dwordx4 v[214:215], off
	s_waitcnt vmcnt(8)
	s_waitcnt lgkmcnt(0)
	s_barrier
; #define PG8_STAGE(bufoff, gbase, voff) do { _Pragma("unroll") for (int _i = 0; _i < 2; ++_i) \
;         __builtin_amdgcn_global_load_lds((const unsigned*)((const char*)(gbase) + (voff)[_i]), (PG8_LAS unsigned*)(lds + (bufoff) + ldsw + _i * 8192), 16, 0, 0); } while (0)
; #define PG8_LDA(dst, b, h) do { _Pragma("unroll") for (int m = 0; m < 4; ++m) _Pragma("unroll") for (int k = 0; k < 2; ++k) dst[m][k] = *(const PG8_LAS bf16x8*)(lds + PG8_SA(b, h) + aoff + m * 2048 + k * 1024); } while (0)
; #define PG8_LDB(dst, b, h) do { _Pragma("unroll") for (int n = 0; n < 2; ++n) _Pragma("unroll") for (int k = 0; k < 2; ++k) dst[n][k] = *(const PG8_LAS bf16x8*)(lds + PG8_SB(b, h) + boff + n * 2048 + k * 1024); } while (0)
; #define PG8_MMA(ai, bj, At, Bt) do { __builtin_amdgcn_s_setprio(1); _Pragma("unroll") for (int m = 0; m < 4; ++m) _Pragma("unroll") for (int n = 0; n < 2; ++n) _Pragma("unroll") for (int k = 0; k < 2; ++k) \
;         acc[ai][bj][m][n] = __builtin_amdgcn_mfma_f32_16x16x32_bf16(Bt[n][k], At[m][k], acc[ai][bj][m][n], 0, 0, 0); __builtin_amdgcn_s_setprio(0); } while (0)
; #define PG8_WAIT_V(n) asm volatile("s_waitcnt vmcnt(" #n ")" ::: "memory")
; #define PG8_WAIT_L(n) asm volatile("s_waitcnt lgkmcnt(" #n ")" ::: "memory")
; #define PG8_BAR __builtin_amdgcn_s_barrier()
; #define PG8_SCHED __builtin_amdgcn_sched_barrier(0)
; template <class Epi, class Sched, bool ALIGN_EPI = false, bool SP2 = false, bool UNIFORM_NT = false>
; __device__ __forceinline__ void gemm_phase(PG8_LAS unsigned char* lds, const Gemm g, const Sched& S, const Epi& E, int tid_in) {
;     ...
;             PG8_WAIT_V(8); PG8_WAIT_L(0); PG8_BAR; PG8_MMA(1, 0, At, B0); PG8_MMA(1, 1, At, B1); PG8_BAR; PG8_SCHED;
;             PG8_LDB(B0, 1, 0); PG8_LDB(B1, 1, 1); PG8_SCHED; PG8_LDA(At, 1, 0); PG8_STAGE(PG8_SA(0, 1), a2 + hstepA, voffA);
;             PG8_WAIT_V(8); PG8_WAIT_L(0); PG8_BAR; PG8_MMA(0, 0, At, B0); PG8_MMA(0, 1, At, B1); PG8_BAR; PG8_SCHED;
;             PG8_LDA(At, 1, 1); PG8_STAGE(PG8_SB(1, 0), b3, voffB); PG8_STAGE(PG8_SB(1, 1), b3 + hstepB, voffB); PG8_STAGE(PG8_SA(1, 0), a3, voffA);
	s_setprio 1
	s_waitcnt lgkmcnt(0)
	v_mfma_f32_16x16x32_bf16 v[62:65], v[146:149], v[178:181], v[62:65]
	v_mfma_f32_16x16x32_bf16 v[58:61], v[154:157], v[178:181], v[58:61]
	v_mfma_f32_16x16x32_bf16 v[46:49], v[146:149], v[186:189], v[46:49]
	v_mfma_f32_16x16x32_bf16 v[42:45], v[154:157], v[186:189], v[42:45]
	v_mfma_f32_16x16x32_bf16 v[30:33], v[146:149], v[194:197], v[30:33]
	v_mfma_f32_16x16x32_bf16 v[26:29], v[154:157], v[194:197], v[26:29]
	v_mfma_f32_16x16x32_bf16 v[14:17], v[146:149], v[202:205], v[14:17]
	v_mfma_f32_16x16x32_bf16 v[10:13], v[154:157], v[202:205], v[10:13]
	v_mfma_f32_16x16x32_bf16 v[62:65], v[150:153], v[182:185], v[62:65]
	v_mfma_f32_16x16x32_bf16 v[58:61], v[158:161], v[182:185], v[58:61]
	v_mfma_f32_16x16x32_bf16 v[46:49], v[150:153], v[190:193], v[46:49]
	v_mfma_f32_16x16x32_bf16 v[42:45], v[158:161], v[190:193], v[42:45]
	v_mfma_f32_16x16x32_bf16 v[30:33], v[150:153], v[198:201], v[30:33]
	v_mfma_f32_16x16x32_bf16 v[26:29], v[158:161], v[198:201], v[26:29]
	v_mfma_f32_16x16x32_bf16 v[14:17], v[150:153], v[206:209], v[14:17]
	v_mfma_f32_16x16x32_bf16 v[10:13], v[158:161], v[206:209], v[10:13]
	v_mfma_f32_16x16x32_bf16 v[54:57], v[162:165], v[178:181], v[54:57]
	v_mfma_f32_16x16x32_bf16 v[50:53], v[170:173], v[178:181], v[50:53]
	v_mfma_f32_16x16x32_bf16 v[38:41], v[162:165], v[186:189], v[38:41]
	v_mfma_f32_16x16x32_bf16 v[34:37], v[170:173], v[186:189], v[34:37]
	v_mfma_f32_16x16x32_bf16 v[22:25], v[162:165], v[194:197], v[22:25]
	v_mfma_f32_16x16x32_bf16 v[18:21], v[170:173], v[194:197], v[18:21]
	v_mfma_f32_16x16x32_bf16 v[6:9], v[162:165], v[202:205], v[6:9]
	v_mfma_f32_16x16x32_bf16 v[2:5], v[170:173], v[202:205], v[2:5]
	v_mfma_f32_16x16x32_bf16 v[54:57], v[166:169], v[182:185], v[54:57]
	v_mfma_f32_16x16x32_bf16 v[50:53], v[174:177], v[182:185], v[50:53]
	v_mfma_f32_16x16x32_bf16 v[38:41], v[166:169], v[190:193], v[38:41]
	v_mfma_f32_16x16x32_bf16 v[34:37], v[174:177], v[190:193], v[34:37]
	v_mfma_f32_16x16x32_bf16 v[22:25], v[166:169], v[198:201], v[22:25]
	v_mfma_f32_16x16x32_bf16 v[18:21], v[174:177], v[198:201], v[18:21]
	v_mfma_f32_16x16x32_bf16 v[6:9], v[166:169], v[206:209], v[6:9]
	v_mfma_f32_16x16x32_bf16 v[2:5], v[174:177], v[206:209], v[2:5]
	s_setprio 0
	s_barrier
	s_add_i32 s47, 0, 0x18000
	s_add_i32 s52, 0, 0x1c000
	v_add_u32_e32 v158, s47, v143
	v_add_u32_e32 v174, s52, v143
	ds_read_b128 v[146:149], v158
	ds_read_b128 v[150:153], v158 offset:1024
	ds_read_b128 v[154:157], v158 offset:2048
	ds_read_b128 v[158:161], v158 offset:3072
	ds_read_b128 v[162:165], v174
	ds_read_b128 v[166:169], v174 offset:1024
	ds_read_b128 v[170:173], v174 offset:2048
	ds_read_b128 v[174:177], v174 offset:3072
	s_add_u32 s48, s58, 0x40000
	s_addc_u32 s49, s59, 0
	s_mov_b32 m0, s9
	v_lshl_add_u64 v[216:217], s[48:49], 0, v[134:135]
	ds_read_b128 v[178:181], v145 offset:32768
	ds_read_b128 v[182:185], v145 offset:33792
	ds_read_b128 v[186:189], v145 offset:34816
	ds_read_b128 v[190:193], v145 offset:35840
	ds_read_b128 v[194:197], v145 offset:36864
	ds_read_b128 v[198:201], v145 offset:37888
	ds_read_b128 v[202:205], v145 offset:38912
	ds_read_b128 v[206:209], v145 offset:39936
	global_load_lds_dwordx4 v[216:217], off
	v_lshl_add_u64 v[216:217], s[48:49], 0, v[132:133]
	s_mov_b32 m0, s14
	s_nop 0
	global_load_lds_dwordx4 v[216:217], off
	s_waitcnt vmcnt(8)
	s_waitcnt lgkmcnt(0)
	s_barrier
	s_setprio 1
	s_waitcnt lgkmcnt(0)
	v_mfma_f32_16x16x32_bf16 v[126:129], v[146:149], v[178:181], v[126:129]
	v_mfma_f32_16x16x32_bf16 v[122:125], v[154:157], v[178:181], v[122:125]
	v_mfma_f32_16x16x32_bf16 v[110:113], v[146:149], v[186:189], v[110:113]
	v_mfma_f32_16x16x32_bf16 v[106:109], v[154:157], v[186:189], v[106:109]
	v_mfma_f32_16x16x32_bf16 v[94:97], v[146:149], v[194:197], v[94:97]
	v_mfma_f32_16x16x32_bf16 v[90:93], v[154:157], v[194:197], v[90:93]
	v_mfma_f32_16x16x32_bf16 v[78:81], v[146:149], v[202:205], v[78:81]
	v_mfma_f32_16x16x32_bf16 v[74:77], v[154:157], v[202:205], v[74:77]
	v_mfma_f32_16x16x32_bf16 v[126:129], v[150:153], v[182:185], v[126:129]
	v_mfma_f32_16x16x32_bf16 v[122:125], v[158:161], v[182:185], v[122:125]
	v_mfma_f32_16x16x32_bf16 v[110:113], v[150:153], v[190:193], v[110:113]
	v_mfma_f32_16x16x32_bf16 v[106:109], v[158:161], v[190:193], v[106:109]
	v_mfma_f32_16x16x32_bf16 v[94:97], v[150:153], v[198:201], v[94:97]
	v_mfma_f32_16x16x32_bf16 v[90:93], v[158:161], v[198:201], v[90:93]
	v_mfma_f32_16x16x32_bf16 v[78:81], v[150:153], v[206:209], v[78:81]
	v_mfma_f32_16x16x32_bf16 v[74:77], v[158:161], v[206:209], v[74:77]
	v_mfma_f32_16x16x32_bf16 v[118:121], v[162:165], v[178:181], v[118:121]
	v_mfma_f32_16x16x32_bf16 v[114:117], v[170:173], v[178:181], v[114:117]
	v_mfma_f32_16x16x32_bf16 v[102:105], v[162:165], v[186:189], v[102:105]
	v_mfma_f32_16x16x32_bf16 v[98:101], v[170:173], v[186:189], v[98:101]
	v_mfma_f32_16x16x32_bf16 v[86:89], v[162:165], v[194:197], v[86:89]
	v_mfma_f32_16x16x32_bf16 v[82:85], v[170:173], v[194:197], v[82:85]
	v_mfma_f32_16x16x32_bf16 v[70:73], v[162:165], v[202:205], v[70:73]
	v_mfma_f32_16x16x32_bf16 v[66:69], v[170:173], v[202:205], v[66:69]
	v_mfma_f32_16x16x32_bf16 v[118:121], v[166:169], v[182:185], v[118:121]
	v_mfma_f32_16x16x32_bf16 v[114:117], v[174:177], v[182:185], v[114:117]
	v_mfma_f32_16x16x32_bf16 v[102:105], v[166:169], v[190:193], v[102:105]
	v_mfma_f32_16x16x32_bf16 v[98:101], v[174:177], v[190:193], v[98:101]
	v_mfma_f32_16x16x32_bf16 v[86:89], v[166:169], v[198:201], v[86:89]
	v_mfma_f32_16x16x32_bf16 v[82:85], v[174:177], v[198:201], v[82:85]
	v_mfma_f32_16x16x32_bf16 v[70:73], v[166:169], v[206:209], v[70:73]
	v_mfma_f32_16x16x32_bf16 v[66:69], v[174:177], v[206:209], v[66:69]
	s_setprio 0
	s_barrier
; #define PG8_STAGE(bufoff, gbase, voff) do { _Pragma("unroll") for (int _i = 0; _i < 2; ++_i) \
;         __builtin_amdgcn_global_load_lds((const unsigned*)((const char*)(gbase) + (voff)[_i]), (PG8_LAS unsigned*)(lds + (bufoff) + ldsw + _i * 8192), 16, 0, 0); } while (0)
; #define PG8_LDA(dst, b, h) do { _Pragma("unroll") for (int m = 0; m < 4; ++m) _Pragma("unroll") for (int k = 0; k < 2; ++k) dst[m][k] = *(const PG8_LAS bf16x8*)(lds + PG8_SA(b, h) + aoff + m * 2048 + k * 1024); } while (0)
; #define PG8_WAIT_V(n) asm volatile("s_waitcnt vmcnt(" #n ")" ::: "memory")
; #define PG8_WAIT_L(n) asm volatile("s_waitcnt lgkmcnt(" #n ")" ::: "memory")
; template <class Epi, class Sched, bool ALIGN_EPI = false, bool SP2 = false, bool UNIFORM_NT = false>
; __device__ __forceinline__ void gemm_phase(PG8_LAS unsigned char* lds, const Gemm g, const Sched& S, const Epi& E, int tid_in) {
;     ...
;         for (int t = 0; t < nt; t += 2) {
;             const bool last = (t == nt - 2);
;             const char* a1 = cA + (size_t)(t + 1) * kstep;
;             const char* a2 = last ? nA : cA + (size_t)(t + 2) * kstep; const char* b2 = last ? nB : cB + (size_t)(t + 2) * kstep;
;             const char* a3 = a2 + kstep; const char* b3 = b2 + kstep;
;             if (last && has_next) S.a_ready(nxt);
;             if constexpr (SP2) {
;             PG8_LDB(B0, 0, 0); PG8_LDB(B1, 0, 1); PG8_SCHED; PG8_LDA(At, 0, 0); PG8_STAGE(PG8_SA(1, 1), a1 + hstepA, voffA);
;             PG8_WAIT_V(8); PG8_WAIT_L(0); PG8_BAR; PG8_MMA(0, 0, At, B0); PG8_MMA(0, 1, At, B1); PG8_BAR; PG8_SCHED;
;             PG8_LDA(At, 0, 1); PG8_STAGE(PG8_SB(0, 0), b2, voffB); PG8_STAGE(PG8_SB(0, 1), b2 + hstepB, voffB); PG8_STAGE(PG8_SA(0, 0), a2, voffA);
;             PG8_WAIT_V(8); PG8_WAIT_L(0); PG8_BAR; PG8_MMA(1, 0, At, B0); PG8_MMA(1, 1, At, B1); PG8_BAR; PG8_SCHED;
;             PG8_LDB(B0, 1, 0); PG8_LDB(B1, 1, 1); PG8_SCHED; PG8_LDA(At, 1, 0); PG8_STAGE(PG8_SA(0, 1), a2 + hstepA, voffA);
;             PG8_WAIT_V(8); PG8_WAIT_L(0); PG8_BAR; PG8_MMA(0, 0, At, B0); PG8_MMA(0, 1, At, B1); PG8_BAR; PG8_SCHED;
;             PG8_LDA(At, 1, 1); PG8_STAGE(PG8_SB(1, 0), b3, voffB); PG8_STAGE(PG8_SB(1, 1), b3 + hstepB, voffB); PG8_STAGE(PG8_SA(1, 0), a3, voffA);
;             PG8_WAIT_V(8); PG8_WAIT_L(0); PG8_BAR; PG8_MMA(1, 0, At, B0); PG8_MMA(1, 1, At, B1); PG8_BAR; PG8_SCHED;
	s_add_i32 s47, s47, s0
	v_lshl_add_u64 v[140:141], v[140:141], 0, s[82:83]
	s_mov_b32 m0, s47
	ds_read_b128 v[178:181], v145 offset:49152
	ds_read_b128 v[182:185], v145 offset:50176
	ds_read_b128 v[186:189], v145 offset:51200
	ds_read_b128 v[190:193], v145 offset:52224
	ds_read_b128 v[194:197], v145 offset:53248
	ds_read_b128 v[198:201], v145 offset:54272
	ds_read_b128 v[202:205], v145 offset:55296
	ds_read_b128 v[206:209], v145 offset:56320
	global_load_lds_dwordx4 v[140:141], off
	s_add_i32 m0, s47, 0x2000
	s_add_u32 s48, s56, 0x40080
	v_lshl_add_u64 v[140:141], v[210:211], 0, s[82:83]
	s_addc_u32 s49, s57, 0
	s_add_i32 s47, s52, s0
	global_load_lds_dwordx4 v[140:141], off
	v_lshl_add_u64 v[140:141], s[48:49], 0, v[0:1]
	s_mov_b32 m0, s47
	s_nop 0
	global_load_lds_dwordx4 v[140:141], off
	v_lshl_add_u64 v[140:141], s[48:49], 0, v[130:131]
	s_add_i32 m0, s47, 0x2000
	s_nop 0
	global_load_lds_dwordx4 v[140:141], off
	v_lshl_add_u64 v[140:141], v[212:213], 0, s[82:83]
	s_mov_b32 m0, s15
	s_nop 0
	global_load_lds_dwordx4 v[140:141], off
	v_lshl_add_u64 v[140:141], v[214:215], 0, s[82:83]
	s_mov_b32 m0, s33
	s_nop 0
	global_load_lds_dwordx4 v[140:141], off
	s_waitcnt vmcnt(8)
	s_waitcnt lgkmcnt(0)
	s_barrier
	s_setprio 1
	s_waitcnt lgkmcnt(0)
	v_mfma_f32_16x16x32_bf16 v[62:65], v[146:149], v[178:181], v[62:65]
	v_mfma_f32_16x16x32_bf16 v[58:61], v[154:157], v[178:181], v[58:61]
	v_mfma_f32_16x16x32_bf16 v[46:49], v[146:149], v[186:189], v[46:49]
	v_mfma_f32_16x16x32_bf16 v[42:45], v[154:157], v[186:189], v[42:45]
	v_mfma_f32_16x16x32_bf16 v[30:33], v[146:149], v[194:197], v[30:33]
	v_mfma_f32_16x16x32_bf16 v[26:29], v[154:157], v[194:197], v[26:29]
	v_mfma_f32_16x16x32_bf16 v[14:17], v[146:149], v[202:205], v[14:17]
	v_mfma_f32_16x16x32_bf16 v[10:13], v[154:157], v[202:205], v[10:13]
	v_mfma_f32_16x16x32_bf16 v[62:65], v[150:153], v[182:185], v[62:65]
	v_mfma_f32_16x16x32_bf16 v[58:61], v[158:161], v[182:185], v[58:61]
	v_mfma_f32_16x16x32_bf16 v[46:49], v[150:153], v[190:193], v[46:49]
	v_mfma_f32_16x16x32_bf16 v[42:45], v[158:161], v[190:193], v[42:45]
	v_mfma_f32_16x16x32_bf16 v[30:33], v[150:153], v[198:201], v[30:33]
	v_mfma_f32_16x16x32_bf16 v[26:29], v[158:161], v[198:201], v[26:29]
	v_mfma_f32_16x16x32_bf16 v[14:17], v[150:153], v[206:209], v[14:17]
	v_mfma_f32_16x16x32_bf16 v[10:13], v[158:161], v[206:209], v[10:13]
	v_mfma_f32_16x16x32_bf16 v[54:57], v[162:165], v[178:181], v[54:57]
	v_mfma_f32_16x16x32_bf16 v[50:53], v[170:173], v[178:181], v[50:53]
	v_mfma_f32_16x16x32_bf16 v[38:41], v[162:165], v[186:189], v[38:41]
	v_mfma_f32_16x16x32_bf16 v[34:37], v[170:173], v[186:189], v[34:37]
	v_mfma_f32_16x16x32_bf16 v[22:25], v[162:165], v[194:197], v[22:25]
	v_mfma_f32_16x16x32_bf16 v[18:21], v[170:173], v[194:197], v[18:21]
	v_mfma_f32_16x16x32_bf16 v[6:9], v[162:165], v[202:205], v[6:9]
	v_mfma_f32_16x16x32_bf16 v[2:5], v[170:173], v[202:205], v[2:5]
	v_mfma_f32_16x16x32_bf16 v[54:57], v[166:169], v[182:185], v[54:57]
	v_mfma_f32_16x16x32_bf16 v[50:53], v[174:177], v[182:185], v[50:53]
	v_mfma_f32_16x16x32_bf16 v[38:41], v[166:169], v[190:193], v[38:41]
	v_mfma_f32_16x16x32_bf16 v[34:37], v[174:177], v[190:193], v[34:37]
	v_mfma_f32_16x16x32_bf16 v[22:25], v[166:169], v[198:201], v[22:25]
	v_mfma_f32_16x16x32_bf16 v[18:21], v[174:177], v[198:201], v[18:21]
	v_mfma_f32_16x16x32_bf16 v[6:9], v[166:169], v[206:209], v[6:9]
	v_mfma_f32_16x16x32_bf16 v[2:5], v[174:177], v[206:209], v[2:5]
	s_setprio 0
	s_barrier
	s_add_i32 s46, s46, 2
	s_add_u32 s54, s54, 0x100
	s_addc_u32 s55, s55, 0
	s_add_u32 s43, s43, 0x100
	s_addc_u32 s45, s45, 0
	s_cmp_gt_u32 s46, 13
	s_cbranch_scc0 .LBB0_54
	s_and_b64 vcc, exec, s[28:29]
	s_cbranch_vccz .LBB0_57
	s_barrier

; #define PG8_STAGE(bufoff, gbase, voff) do { _Pragma("unroll") for (int _i = 0; _i < 2; ++_i) \
;         __builtin_amdgcn_global_load_lds((const unsigned*)((const char*)(gbase) + (voff)[_i]), (PG8_LAS unsigned*)(lds + (bufoff) + ldsw + _i * 8192), 16, 0, 0); } while (0)
; #define PG8_LDA(dst, b, h) do { _Pragma("unroll") for (int m = 0; m < 4; ++m) _Pragma("unroll") for (int k = 0; k < 2; ++k) dst[m][k] = *(const PG8_LAS bf16x8*)(lds + PG8_SA(b, h) + aoff + m * 2048 + k * 1024); } while (0)
; #define PG8_LDB(dst, b, h) do { _Pragma("unroll") for (int n = 0; n < 2; ++n) _Pragma("unroll") for (int k = 0; k < 2; ++k) dst[n][k] = *(const PG8_LAS bf16x8*)(lds + PG8_SB(b, h) + boff + n * 2048 + k * 1024); } while (0)
; #define PG8_MMA(ai, bj, At, Bt) do { __builtin_amdgcn_s_setprio(1); _Pragma("unroll") for (int m = 0; m < 4; ++m) _Pragma("unroll") for (int n = 0; n < 2; ++n) _Pragma("unroll") for (int k = 0; k < 2; ++k) \
;         acc[ai][bj][m][n] = __builtin_amdgcn_mfma_f32_16x16x32_bf16(Bt[n][k], At[m][k], acc[ai][bj][m][n], 0, 0, 0); __builtin_amdgcn_s_setprio(0); } while (0)
; #define PG8_WAIT_V(n) asm volatile("s_waitcnt vmcnt(" #n ")" ::: "memory")
; #define PG8_WAIT_L(n) asm volatile("s_waitcnt lgkmcnt(" #n ")" ::: "memory")
; #define PG8_BAR __builtin_amdgcn_s_barrier()
; #define PG8_SCHED __builtin_amdgcn_sched_barrier(0)
; template <class Epi, class Sched, bool ALIGN_EPI = false, bool SP2 = false, bool UNIFORM_NT = false>
; __device__ __forceinline__ void gemm_phase(PG8_LAS unsigned char* lds, const Gemm g, const Sched& S, const Epi& E, int tid_in) {
;     ...
;             PG8_LDB(B0, 0, 0); PG8_LDB(B1, 0, 1); PG8_SCHED; PG8_LDA(At, 0, 0); PG8_STAGE(PG8_SA(1, 1), a1 + hstepA, voffA);
;             PG8_WAIT_V(8); PG8_WAIT_L(0); PG8_BAR; PG8_MMA(0, 0, At, B0); PG8_MMA(0, 1, At, B1); PG8_BAR; PG8_SCHED;
;             PG8_LDA(At, 0, 1); PG8_STAGE(PG8_SB(0, 0), b2, voffB); PG8_STAGE(PG8_SB(0, 1), b2 + hstepB, voffB); PG8_STAGE(PG8_SA(0, 0), a2, voffA);
;             PG8_WAIT_V(8); PG8_WAIT_L(0); PG8_BAR; PG8_MMA(1, 0, At, B0); PG8_MMA(1, 1, At, B1); PG8_BAR; PG8_SCHED;
.LBB0_112:
	s_add_i32 s37, s35, 2
	s_add_u32 s40, s10, 0x80
	s_addc_u32 s41, s11, 0
	s_add_i32 s43, 0, 0x10000
	s_cmp_eq_u32 s12, s35
	s_cselect_b32 s41, s85, s41
	s_cselect_b32 s40, s84, s40
	s_cselect_b32 s45, s69, s31
	s_cselect_b32 s44, s68, s13
	s_add_i32 s35, 0, 0x14000
	v_add_u32_e32 v142, s43, v243
	v_add_u32_e32 v158, s35, v243
	ds_read_b128 v[130:133], v142
	ds_read_b128 v[134:137], v142 offset:1024
	ds_read_b128 v[138:141], v142 offset:2048
	ds_read_b128 v[142:145], v142 offset:3072
	ds_read_b128 v[146:149], v158
	ds_read_b128 v[150:153], v158 offset:1024
	ds_read_b128 v[154:157], v158 offset:2048
	ds_read_b128 v[158:161], v158 offset:3072
	v_lshl_add_u64 v[204:205], s[10:11], 0, v[184:185]
	s_add_i32 m0, s64, 0xc000
	ds_read_b128 v[162:165], v244
	ds_read_b128 v[166:169], v244 offset:1024
	ds_read_b128 v[170:173], v244 offset:2048
	ds_read_b128 v[174:177], v244 offset:3072
	ds_read_b128 v[188:191], v244 offset:4096
	ds_read_b128 v[192:195], v244 offset:5120
	ds_read_b128 v[196:199], v244 offset:6144
	ds_read_b128 v[200:203], v244 offset:7168
	global_load_lds_dwordx4 v[204:205], off
	v_lshl_add_u64 v[204:205], s[10:11], 0, v[186:187]
	s_add_i32 m0, s64, 0xe000
	s_nop 0
	global_load_lds_dwordx4 v[204:205], off
	s_waitcnt vmcnt(8)
	s_waitcnt lgkmcnt(0)
	s_barrier
	s_setprio 1
	s_waitcnt lgkmcnt(0)
	v_mfma_f32_16x16x32_bf16 v[126:129], v[130:133], v[162:165], v[126:129]
	v_mfma_f32_16x16x32_bf16 v[122:125], v[138:141], v[162:165], v[122:125]
	v_mfma_f32_16x16x32_bf16 v[118:121], v[130:133], v[170:173], v[118:121]
	v_mfma_f32_16x16x32_bf16 v[114:117], v[138:141], v[170:173], v[114:117]
	v_mfma_f32_16x16x32_bf16 v[110:113], v[130:133], v[188:191], v[110:113]
	v_mfma_f32_16x16x32_bf16 v[106:109], v[138:141], v[188:191], v[106:109]
	v_mfma_f32_16x16x32_bf16 v[102:105], v[130:133], v[196:199], v[102:105]
	v_mfma_f32_16x16x32_bf16 v[98:101], v[138:141], v[196:199], v[98:101]
	v_mfma_f32_16x16x32_bf16 v[126:129], v[134:137], v[166:169], v[126:129]
	v_mfma_f32_16x16x32_bf16 v[122:125], v[142:145], v[166:169], v[122:125]
	v_mfma_f32_16x16x32_bf16 v[118:121], v[134:137], v[174:177], v[118:121]
	v_mfma_f32_16x16x32_bf16 v[114:117], v[142:145], v[174:177], v[114:117]
	v_mfma_f32_16x16x32_bf16 v[110:113], v[134:137], v[192:195], v[110:113]
	v_mfma_f32_16x16x32_bf16 v[106:109], v[142:145], v[192:195], v[106:109]
	v_mfma_f32_16x16x32_bf16 v[102:105], v[134:137], v[200:203], v[102:105]
	v_mfma_f32_16x16x32_bf16 v[98:101], v[142:145], v[200:203], v[98:101]
	v_mfma_f32_16x16x32_bf16 v[62:65], v[146:149], v[162:165], v[62:65]
	v_mfma_f32_16x16x32_bf16 v[58:61], v[154:157], v[162:165], v[58:61]
	v_mfma_f32_16x16x32_bf16 v[54:57], v[146:149], v[170:173], v[54:57]
	v_mfma_f32_16x16x32_bf16 v[50:53], v[154:157], v[170:173], v[50:53]
	v_mfma_f32_16x16x32_bf16 v[46:49], v[146:149], v[188:191], v[46:49]
	v_mfma_f32_16x16x32_bf16 v[42:45], v[154:157], v[188:191], v[42:45]
	v_mfma_f32_16x16x32_bf16 v[38:41], v[146:149], v[196:199], v[38:41]
	v_mfma_f32_16x16x32_bf16 v[34:37], v[154:157], v[196:199], v[34:37]
	v_mfma_f32_16x16x32_bf16 v[62:65], v[150:153], v[166:169], v[62:65]
	v_mfma_f32_16x16x32_bf16 v[58:61], v[158:161], v[166:169], v[58:61]
	v_mfma_f32_16x16x32_bf16 v[54:57], v[150:153], v[174:177], v[54:57]
	v_mfma_f32_16x16x32_bf16 v[50:53], v[158:161], v[174:177], v[50:53]
	v_mfma_f32_16x16x32_bf16 v[46:49], v[150:153], v[192:195], v[46:49]
	v_mfma_f32_16x16x32_bf16 v[42:45], v[158:161], v[192:195], v[42:45]
	v_mfma_f32_16x16x32_bf16 v[38:41], v[150:153], v[200:203], v[38:41]
	v_mfma_f32_16x16x32_bf16 v[34:37], v[158:161], v[200:203], v[34:37]
	s_setprio 0
	s_barrier
	s_add_i32 s43, s43, s49
	v_lshl_add_u64 v[204:205], s[44:45], 0, v[0:1]
	s_mov_b32 m0, s43
	ds_read_b128 v[162:165], v244 offset:16384
	ds_read_b128 v[166:169], v244 offset:17408
	ds_read_b128 v[170:173], v244 offset:18432
	ds_read_b128 v[174:177], v244 offset:19456
	ds_read_b128 v[188:191], v244 offset:20480
	ds_read_b128 v[192:195], v244 offset:21504
	ds_read_b128 v[196:199], v244 offset:22528
	ds_read_b128 v[200:203], v244 offset:23552
	global_load_lds_dwordx4 v[204:205], off
	s_add_i32 m0, s43, 0x2000
	v_lshl_add_u64 v[206:207], s[44:45], 0, v[182:183]
	s_add_u32 s44, s44, s26
	s_addc_u32 s45, s45, 0
	s_add_i32 s35, s35, s49
	global_load_lds_dwordx4 v[206:207], off
	v_lshl_add_u64 v[208:209], s[44:45], 0, v[0:1]
	s_mov_b32 m0, s35
	v_lshl_add_u64 v[210:211], s[44:45], 0, v[182:183]
	global_load_lds_dwordx4 v[208:209], off
	s_add_i32 m0, s35, 0x2000
	v_lshl_add_u64 v[212:213], s[40:41], 0, v[178:179]
	global_load_lds_dwordx4 v[210:211], off
	s_mov_b32 m0, s64
	v_lshl_add_u64 v[214:215], s[40:41], 0, v[180:181]
	global_load_lds_dwordx4 v[212:213], off
	s_mov_b32 m0, s78
	s_nop 0
	global_load_lds_dwordx4 v[214:215], off
	s_waitcnt vmcnt(8)
	s_waitcnt lgkmcnt(0)
	s_barrier
; #define PG8_STAGE(bufoff, gbase, voff) do { _Pragma("unroll") for (int _i = 0; _i < 2; ++_i) \
;         __builtin_amdgcn_global_load_lds((const unsigned*)((const char*)(gbase) + (voff)[_i]), (PG8_LAS unsigned*)(lds + (bufoff) + ldsw + _i * 8192), 16, 0, 0); } while (0)
; #define PG8_LDA(dst, b, h) do { _Pragma("unroll") for (int m = 0; m < 4; ++m) _Pragma("unroll") for (int k = 0; k < 2; ++k) dst[m][k] = *(const PG8_LAS bf16x8*)(lds + PG8_SA(b, h) + aoff + m * 2048 + k * 1024); } while (0)
; #define PG8_LDB(dst, b, h) do { _Pragma("unroll") for (int n = 0; n < 2; ++n) _Pragma("unroll") for (int k = 0; k < 2; ++k) dst[n][k] = *(const PG8_LAS bf16x8*)(lds + PG8_SB(b, h) + boff + n * 2048 + k * 1024); } while (0)
; #define PG8_MMA(ai, bj, At, Bt) do { __builtin_amdgcn_s_setprio(1); _Pragma("unroll") for (int m = 0; m < 4; ++m) _Pragma("unroll") for (int n = 0; n < 2; ++n) _Pragma("unroll") for (int k = 0; k < 2; ++k) \
;         acc[ai][bj][m][n] = __builtin_amdgcn_mfma_f32_16x16x32_bf16(Bt[n][k], At[m][k], acc[ai][bj][m][n], 0, 0, 0); __builtin_amdgcn_s_setprio(0); } while (0)
; #define PG8_WAIT_V(n) asm volatile("s_waitcnt vmcnt(" #n ")" ::: "memory")
; #define PG8_WAIT_L(n) asm volatile("s_waitcnt lgkmcnt(" #n ")" ::: "memory")
; #define PG8_BAR __builtin_amdgcn_s_barrier()
; #define PG8_SCHED __builtin_amdgcn_sched_barrier(0)
; template <class Epi, class Sched, bool ALIGN_EPI = false, bool SP2 = false, bool UNIFORM_NT = false>
; __device__ __forceinline__ void gemm_phase(PG8_LAS unsigned char* lds, const Gemm g, const Sched& S, const Epi& E, int tid_in) {
;     ...
;             PG8_WAIT_V(8); PG8_WAIT_L(0); PG8_BAR; PG8_MMA(1, 0, At, B0); PG8_MMA(1, 1, At, B1); PG8_BAR; PG8_SCHED;
;             PG8_LDB(B0, 1, 0); PG8_LDB(B1, 1, 1); PG8_SCHED; PG8_LDA(At, 1, 0); PG8_STAGE(PG8_SA(0, 1), a2 + hstepA, voffA);
;             PG8_WAIT_V(8); PG8_WAIT_L(0); PG8_BAR; PG8_MMA(0, 0, At, B0); PG8_MMA(0, 1, At, B1); PG8_BAR; PG8_SCHED;
;             PG8_LDA(At, 1, 1); PG8_STAGE(PG8_SB(1, 0), b3, voffB); PG8_STAGE(PG8_SB(1, 1), b3 + hstepB, voffB); PG8_STAGE(PG8_SA(1, 0), a3, voffA);
	s_setprio 1
	s_waitcnt lgkmcnt(0)
	v_mfma_f32_16x16x32_bf16 v[94:97], v[130:133], v[162:165], v[94:97]
	v_mfma_f32_16x16x32_bf16 v[90:93], v[138:141], v[162:165], v[90:93]
	v_mfma_f32_16x16x32_bf16 v[86:89], v[130:133], v[170:173], v[86:89]
	v_mfma_f32_16x16x32_bf16 v[82:85], v[138:141], v[170:173], v[82:85]
	v_mfma_f32_16x16x32_bf16 v[78:81], v[130:133], v[188:191], v[78:81]
	v_mfma_f32_16x16x32_bf16 v[74:77], v[138:141], v[188:191], v[74:77]
	v_mfma_f32_16x16x32_bf16 v[70:73], v[130:133], v[196:199], v[70:73]
	v_mfma_f32_16x16x32_bf16 v[66:69], v[138:141], v[196:199], v[66:69]
	v_mfma_f32_16x16x32_bf16 v[94:97], v[134:137], v[166:169], v[94:97]
	v_mfma_f32_16x16x32_bf16 v[90:93], v[142:145], v[166:169], v[90:93]
	v_mfma_f32_16x16x32_bf16 v[86:89], v[134:137], v[174:177], v[86:89]
	v_mfma_f32_16x16x32_bf16 v[82:85], v[142:145], v[174:177], v[82:85]
	v_mfma_f32_16x16x32_bf16 v[78:81], v[134:137], v[192:195], v[78:81]
	v_mfma_f32_16x16x32_bf16 v[74:77], v[142:145], v[192:195], v[74:77]
	v_mfma_f32_16x16x32_bf16 v[70:73], v[134:137], v[200:203], v[70:73]
	v_mfma_f32_16x16x32_bf16 v[66:69], v[142:145], v[200:203], v[66:69]
	v_mfma_f32_16x16x32_bf16 v[30:33], v[146:149], v[162:165], v[30:33]
	v_mfma_f32_16x16x32_bf16 v[26:29], v[154:157], v[162:165], v[26:29]
	v_mfma_f32_16x16x32_bf16 v[22:25], v[146:149], v[170:173], v[22:25]
	v_mfma_f32_16x16x32_bf16 v[18:21], v[154:157], v[170:173], v[18:21]
	v_mfma_f32_16x16x32_bf16 v[14:17], v[146:149], v[188:191], v[14:17]
	v_mfma_f32_16x16x32_bf16 v[10:13], v[154:157], v[188:191], v[10:13]
	v_mfma_f32_16x16x32_bf16 v[6:9], v[146:149], v[196:199], v[6:9]
	v_mfma_f32_16x16x32_bf16 v[2:5], v[154:157], v[196:199], v[2:5]
	v_mfma_f32_16x16x32_bf16 v[30:33], v[150:153], v[166:169], v[30:33]
	v_mfma_f32_16x16x32_bf16 v[26:29], v[158:161], v[166:169], v[26:29]
	v_mfma_f32_16x16x32_bf16 v[22:25], v[150:153], v[174:177], v[22:25]
	v_mfma_f32_16x16x32_bf16 v[18:21], v[158:161], v[174:177], v[18:21]
	v_mfma_f32_16x16x32_bf16 v[14:17], v[150:153], v[192:195], v[14:17]
	v_mfma_f32_16x16x32_bf16 v[10:13], v[158:161], v[192:195], v[10:13]
	v_mfma_f32_16x16x32_bf16 v[6:9], v[150:153], v[200:203], v[6:9]
	v_mfma_f32_16x16x32_bf16 v[2:5], v[158:161], v[200:203], v[2:5]
	s_setprio 0
	s_barrier
	s_add_i32 s35, 0, 0x18000
	s_add_i32 s43, 0, 0x1c000
	v_add_u32_e32 v142, s35, v243
	v_add_u32_e32 v158, s43, v243
	ds_read_b128 v[130:133], v142
	ds_read_b128 v[134:137], v142 offset:1024
	ds_read_b128 v[138:141], v142 offset:2048
	ds_read_b128 v[142:145], v142 offset:3072
	ds_read_b128 v[146:149], v158
	ds_read_b128 v[150:153], v158 offset:1024
	ds_read_b128 v[154:157], v158 offset:2048
	ds_read_b128 v[158:161], v158 offset:3072
	s_add_u32 s40, s40, s26
	s_addc_u32 s41, s41, 0
	s_mov_b32 m0, s79
	v_lshl_add_u64 v[216:217], s[40:41], 0, v[178:179]
	ds_read_b128 v[162:165], v244 offset:32768
	ds_read_b128 v[166:169], v244 offset:33792
	ds_read_b128 v[170:173], v244 offset:34816
	ds_read_b128 v[174:177], v244 offset:35840
	ds_read_b128 v[188:191], v244 offset:36864
	ds_read_b128 v[192:195], v244 offset:37888
	ds_read_b128 v[196:199], v244 offset:38912
	ds_read_b128 v[200:203], v244 offset:39936
	global_load_lds_dwordx4 v[216:217], off
	v_lshl_add_u64 v[216:217], s[40:41], 0, v[180:181]
	s_mov_b32 m0, s88
	s_nop 0
	global_load_lds_dwordx4 v[216:217], off
	s_waitcnt vmcnt(8)
	s_waitcnt lgkmcnt(0)
	s_barrier
	s_setprio 1
	s_waitcnt lgkmcnt(0)
	v_mfma_f32_16x16x32_bf16 v[126:129], v[130:133], v[162:165], v[126:129]
	v_mfma_f32_16x16x32_bf16 v[122:125], v[138:141], v[162:165], v[122:125]
	v_mfma_f32_16x16x32_bf16 v[118:121], v[130:133], v[170:173], v[118:121]
	v_mfma_f32_16x16x32_bf16 v[114:117], v[138:141], v[170:173], v[114:117]
	v_mfma_f32_16x16x32_bf16 v[110:113], v[130:133], v[188:191], v[110:113]
	v_mfma_f32_16x16x32_bf16 v[106:109], v[138:141], v[188:191], v[106:109]
	v_mfma_f32_16x16x32_bf16 v[102:105], v[130:133], v[196:199], v[102:105]
	v_mfma_f32_16x16x32_bf16 v[98:101], v[138:141], v[196:199], v[98:101]
	v_mfma_f32_16x16x32_bf16 v[126:129], v[134:137], v[166:169], v[126:129]
	v_mfma_f32_16x16x32_bf16 v[122:125], v[142:145], v[166:169], v[122:125]
	v_mfma_f32_16x16x32_bf16 v[118:121], v[134:137], v[174:177], v[118:121]
	v_mfma_f32_16x16x32_bf16 v[114:117], v[142:145], v[174:177], v[114:117]
	v_mfma_f32_16x16x32_bf16 v[110:113], v[134:137], v[192:195], v[110:113]
	v_mfma_f32_16x16x32_bf16 v[106:109], v[142:145], v[192:195], v[106:109]
	v_mfma_f32_16x16x32_bf16 v[102:105], v[134:137], v[200:203], v[102:105]
	v_mfma_f32_16x16x32_bf16 v[98:101], v[142:145], v[200:203], v[98:101]
	v_mfma_f32_16x16x32_bf16 v[62:65], v[146:149], v[162:165], v[62:65]
	v_mfma_f32_16x16x32_bf16 v[58:61], v[154:157], v[162:165], v[58:61]
	v_mfma_f32_16x16x32_bf16 v[54:57], v[146:149], v[170:173], v[54:57]
	v_mfma_f32_16x16x32_bf16 v[50:53], v[154:157], v[170:173], v[50:53]
	v_mfma_f32_16x16x32_bf16 v[46:49], v[146:149], v[188:191], v[46:49]
	v_mfma_f32_16x16x32_bf16 v[42:45], v[154:157], v[188:191], v[42:45]
	v_mfma_f32_16x16x32_bf16 v[38:41], v[146:149], v[196:199], v[38:41]
	v_mfma_f32_16x16x32_bf16 v[34:37], v[154:157], v[196:199], v[34:37]
	v_mfma_f32_16x16x32_bf16 v[62:65], v[150:153], v[166:169], v[62:65]
	v_mfma_f32_16x16x32_bf16 v[58:61], v[158:161], v[166:169], v[58:61]
	v_mfma_f32_16x16x32_bf16 v[54:57], v[150:153], v[174:177], v[54:57]
	v_mfma_f32_16x16x32_bf16 v[50:53], v[158:161], v[174:177], v[50:53]
	v_mfma_f32_16x16x32_bf16 v[46:49], v[150:153], v[192:195], v[46:49]
	v_mfma_f32_16x16x32_bf16 v[42:45], v[158:161], v[192:195], v[42:45]
	v_mfma_f32_16x16x32_bf16 v[38:41], v[150:153], v[200:203], v[38:41]
	v_mfma_f32_16x16x32_bf16 v[34:37], v[158:161], v[200:203], v[34:37]
	s_setprio 0
	s_barrier
; #define PG8_STAGE(bufoff, gbase, voff) do { _Pragma("unroll") for (int _i = 0; _i < 2; ++_i) \
;         __builtin_amdgcn_global_load_lds((const unsigned*)((const char*)(gbase) + (voff)[_i]), (PG8_LAS unsigned*)(lds + (bufoff) + ldsw + _i * 8192), 16, 0, 0); } while (0)
; #define PG8_LDA(dst, b, h) do { _Pragma("unroll") for (int m = 0; m < 4; ++m) _Pragma("unroll") for (int k = 0; k < 2; ++k) dst[m][k] = *(const PG8_LAS bf16x8*)(lds + PG8_SA(b, h) + aoff + m * 2048 + k * 1024); } while (0)
; #define PG8_LDB(dst, b, h) do { _Pragma("unroll") for (int n = 0; n < 2; ++n) _Pragma("unroll") for (int k = 0; k < 2; ++k) dst[n][k] = *(const PG8_LAS bf16x8*)(lds + PG8_SB(b, h) + boff + n * 2048 + k * 1024); } while (0)
; #define PG8_MMA(ai, bj, At, Bt) do { __builtin_amdgcn_s_setprio(1); _Pragma("unroll") for (int m = 0; m < 4; ++m) _Pragma("unroll") for (int n = 0; n < 2; ++n) _Pragma("unroll") for (int k = 0; k < 2; ++k) \
;         acc[ai][bj][m][n] = __builtin_amdgcn_mfma_f32_16x16x32_bf16(Bt[n][k], At[m][k], acc[ai][bj][m][n], 0, 0, 0); __builtin_amdgcn_s_setprio(0); } while (0)
; template <class Epi, class Sched, bool ALIGN_EPI = false, bool SP2 = false, bool UNIFORM_NT = false>
; __device__ __forceinline__ void gemm_phase(PG8_LAS unsigned char* lds, const Gemm g, const Sched& S, const Epi& E, int tid_in) {
;     ...
;             PG8_LDB(B0, 0, 0); PG8_LDB(B1, 0, 1); PG8_SCHED; PG8_LDA(At, 0, 0); PG8_STAGE(PG8_SA(1, 1), a1 + hstepA, voffA);
;             PG8_WAIT_V(8); PG8_WAIT_L(0); PG8_BAR; PG8_MMA(0, 0, At, B0); PG8_MMA(0, 1, At, B1); PG8_BAR; PG8_SCHED;
;             PG8_LDA(At, 0, 1); PG8_STAGE(PG8_SB(0, 0), b2, voffB); PG8_STAGE(PG8_SB(0, 1), b2 + hstepB, voffB); PG8_STAGE(PG8_SA(0, 0), a2, voffA);
;             PG8_WAIT_V(8); PG8_WAIT_L(0); PG8_BAR; PG8_MMA(1, 0, At, B0); PG8_MMA(1, 1, At, B1); PG8_BAR; PG8_SCHED;
;             PG8_LDB(B0, 1, 0); PG8_LDB(B1, 1, 1); PG8_SCHED; PG8_LDA(At, 1, 0); PG8_STAGE(PG8_SA(0, 1), a2 + hstepA, voffA);
;             PG8_WAIT_V(8); PG8_WAIT_L(0); PG8_BAR; PG8_MMA(0, 0, At, B0); PG8_MMA(0, 1, At, B1); PG8_BAR; PG8_SCHED;
;             PG8_LDA(At, 1, 1); PG8_STAGE(PG8_SB(1, 0), b3, voffB); PG8_STAGE(PG8_SB(1, 1), b3 + hstepB, voffB); PG8_STAGE(PG8_SA(1, 0), a3, voffA);
;             PG8_WAIT_V(8); PG8_WAIT_L(0); PG8_BAR; PG8_MMA(1, 0, At, B0); PG8_MMA(1, 1, At, B1); PG8_BAR; PG8_SCHED;
	s_add_i32 s35, s35, s49
	v_lshl_add_u64 v[204:205], v[204:205], 0, s[82:83]
	s_mov_b32 m0, s35
	ds_read_b128 v[162:165], v244 offset:49152
	ds_read_b128 v[166:169], v244 offset:50176
	ds_read_b128 v[170:173], v244 offset:51200
	ds_read_b128 v[174:177], v244 offset:52224
	ds_read_b128 v[188:191], v244 offset:53248
	ds_read_b128 v[192:195], v244 offset:54272
	ds_read_b128 v[196:199], v244 offset:55296
	ds_read_b128 v[200:203], v244 offset:56320
	global_load_lds_dwordx4 v[204:205], off
	v_lshl_add_u64 v[204:205], v[206:207], 0, s[82:83]
	s_add_i32 m0, s35, 0x2000
	s_add_i32 s35, s43, s49
	global_load_lds_dwordx4 v[204:205], off
	v_lshl_add_u64 v[204:205], v[208:209], 0, s[82:83]
	s_mov_b32 m0, s35
	s_nop 0
	global_load_lds_dwordx4 v[204:205], off
	v_lshl_add_u64 v[204:205], v[210:211], 0, s[82:83]
	s_add_i32 m0, s35, 0x2000
	s_nop 0
	global_load_lds_dwordx4 v[204:205], off
	v_lshl_add_u64 v[204:205], v[212:213], 0, s[82:83]
	s_mov_b32 m0, s94
	s_nop 0
	global_load_lds_dwordx4 v[204:205], off
	v_lshl_add_u64 v[204:205], v[214:215], 0, s[82:83]
	s_mov_b32 m0, s89
	s_nop 0
	global_load_lds_dwordx4 v[204:205], off
	s_waitcnt vmcnt(8)
	s_waitcnt lgkmcnt(0)
	s_barrier
	s_setprio 1
	s_waitcnt lgkmcnt(0)
	v_mfma_f32_16x16x32_bf16 v[94:97], v[130:133], v[162:165], v[94:97]
	v_mfma_f32_16x16x32_bf16 v[90:93], v[138:141], v[162:165], v[90:93]
	v_mfma_f32_16x16x32_bf16 v[86:89], v[130:133], v[170:173], v[86:89]
	v_mfma_f32_16x16x32_bf16 v[82:85], v[138:141], v[170:173], v[82:85]
	v_mfma_f32_16x16x32_bf16 v[78:81], v[130:133], v[188:191], v[78:81]
	v_mfma_f32_16x16x32_bf16 v[74:77], v[138:141], v[188:191], v[74:77]
	v_mfma_f32_16x16x32_bf16 v[70:73], v[130:133], v[196:199], v[70:73]
	v_mfma_f32_16x16x32_bf16 v[66:69], v[138:141], v[196:199], v[66:69]
	v_mfma_f32_16x16x32_bf16 v[94:97], v[134:137], v[166:169], v[94:97]
	v_mfma_f32_16x16x32_bf16 v[90:93], v[142:145], v[166:169], v[90:93]
	v_mfma_f32_16x16x32_bf16 v[86:89], v[134:137], v[174:177], v[86:89]
	v_mfma_f32_16x16x32_bf16 v[82:85], v[142:145], v[174:177], v[82:85]
	v_mfma_f32_16x16x32_bf16 v[78:81], v[134:137], v[192:195], v[78:81]
	v_mfma_f32_16x16x32_bf16 v[74:77], v[142:145], v[192:195], v[74:77]
	v_mfma_f32_16x16x32_bf16 v[70:73], v[134:137], v[200:203], v[70:73]
	v_mfma_f32_16x16x32_bf16 v[66:69], v[142:145], v[200:203], v[66:69]
	v_mfma_f32_16x16x32_bf16 v[30:33], v[146:149], v[162:165], v[30:33]
	v_mfma_f32_16x16x32_bf16 v[26:29], v[154:157], v[162:165], v[26:29]
	v_mfma_f32_16x16x32_bf16 v[22:25], v[146:149], v[170:173], v[22:25]
	v_mfma_f32_16x16x32_bf16 v[18:21], v[154:157], v[170:173], v[18:21]
	v_mfma_f32_16x16x32_bf16 v[14:17], v[146:149], v[188:191], v[14:17]
	v_mfma_f32_16x16x32_bf16 v[10:13], v[154:157], v[188:191], v[10:13]
	v_mfma_f32_16x16x32_bf16 v[6:9], v[146:149], v[196:199], v[6:9]
	v_mfma_f32_16x16x32_bf16 v[2:5], v[154:157], v[196:199], v[2:5]
	v_mfma_f32_16x16x32_bf16 v[30:33], v[150:153], v[166:169], v[30:33]
	v_mfma_f32_16x16x32_bf16 v[26:29], v[158:161], v[166:169], v[26:29]
	v_mfma_f32_16x16x32_bf16 v[22:25], v[150:153], v[174:177], v[22:25]
	v_mfma_f32_16x16x32_bf16 v[18:21], v[158:161], v[174:177], v[18:21]
	v_mfma_f32_16x16x32_bf16 v[14:17], v[150:153], v[192:195], v[14:17]
	v_mfma_f32_16x16x32_bf16 v[10:13], v[158:161], v[192:195], v[10:13]
	v_mfma_f32_16x16x32_bf16 v[6:9], v[150:153], v[200:203], v[6:9]
	v_mfma_f32_16x16x32_bf16 v[2:5], v[158:161], v[200:203], v[2:5]
	s_setprio 0
	s_barrier
	s_add_u32 s10, s10, 0x100
	s_addc_u32 s11, s11, 0
	s_add_u32 s13, s13, 0x100
	s_addc_u32 s31, s31, 0
	s_cmp_ge_i32 s37, s15
	s_mov_b32 s35, s37
	s_cbranch_scc0 .LBB0_112
	s_and_b64 vcc, exec, s[62:63]
	s_cbranch_vccz .LBB0_115
	s_barrier

; #define PG8_STAGE(bufoff, gbase, voff) do { _Pragma("unroll") for (int _i = 0; _i < 2; ++_i) \
;         __builtin_amdgcn_global_load_lds((const unsigned*)((const char*)(gbase) + (voff)[_i]), (PG8_LAS unsigned*)(lds + (bufoff) + ldsw + _i * 8192), 16, 0, 0); } while (0)
; #define PG8_LDA(dst, b, h) do { _Pragma("unroll") for (int m = 0; m < 4; ++m) _Pragma("unroll") for (int k = 0; k < 2; ++k) dst[m][k] = *(const PG8_LAS bf16x8*)(lds + PG8_SA(b, h) + aoff + m * 2048 + k * 1024); } while (0)
; #define PG8_LDB(dst, b, h) do { _Pragma("unroll") for (int n = 0; n < 2; ++n) _Pragma("unroll") for (int k = 0; k < 2; ++k) dst[n][k] = *(const PG8_LAS bf16x8*)(lds + PG8_SB(b, h) + boff + n * 2048 + k * 1024); } while (0)
; #define PG8_MMA(ai, bj, At, Bt) do { __builtin_amdgcn_s_setprio(1); _Pragma("unroll") for (int m = 0; m < 4; ++m) _Pragma("unroll") for (int n = 0; n < 2; ++n) _Pragma("unroll") for (int k = 0; k < 2; ++k) \
;         acc[ai][bj][m][n] = __builtin_amdgcn_mfma_f32_16x16x32_bf16(Bt[n][k], At[m][k], acc[ai][bj][m][n], 0, 0, 0); __builtin_amdgcn_s_setprio(0); } while (0)
; #define PG8_WAIT_V(n) asm volatile("s_waitcnt vmcnt(" #n ")" ::: "memory")
; #define PG8_WAIT_L(n) asm volatile("s_waitcnt lgkmcnt(" #n ")" ::: "memory")
; #define PG8_BAR __builtin_amdgcn_s_barrier()
; #define PG8_SCHED __builtin_amdgcn_sched_barrier(0)
; template <class Epi, class Sched, bool ALIGN_EPI = false, bool SP2 = false, bool UNIFORM_NT = false>
; __device__ __forceinline__ void gemm_phase(PG8_LAS unsigned char* lds, const Gemm g, const Sched& S, const Epi& E, int tid_in) {
;     ...
;             PG8_LDB(B0, 0, 0); PG8_LDB(B1, 0, 1); PG8_SCHED; PG8_LDA(At, 0, 0); PG8_STAGE(PG8_SA(1, 1), a1 + hstepA, voffA);
;             PG8_WAIT_V(8); PG8_WAIT_L(0); PG8_BAR; PG8_MMA(0, 0, At, B0); PG8_MMA(0, 1, At, B1); PG8_BAR; PG8_SCHED;
;             PG8_LDA(At, 0, 1); PG8_STAGE(PG8_SB(0, 0), b2, voffB); PG8_STAGE(PG8_SB(0, 1), b2 + hstepB, voffB); PG8_STAGE(PG8_SA(0, 0), a2, voffA);
;             PG8_WAIT_V(8); PG8_WAIT_L(0); PG8_BAR; PG8_MMA(1, 0, At, B0); PG8_MMA(1, 1, At, B1); PG8_BAR; PG8_SCHED;
.LBB0_833:
	s_add_u32 s26, s24, 0xfffc0080
	s_addc_u32 s27, s25, -1
	s_add_i32 s40, 0, 0x10000
	s_cmp_eq_u32 s37, 12
	s_cselect_b32 s29, s11, s27
	s_cselect_b32 s28, s12, s26
	s_cselect_b32 s27, s13, s36
	s_cselect_b32 s26, s19, s35
	s_add_i32 s42, 0, 0x14000
	v_add_u32_e32 v156, s40, v145
	v_add_u32_e32 v164, s42, v145
	ds_read_b128 v[140:143], v156
	ds_read_b128 v[148:151], v156 offset:1024
	ds_read_b128 v[152:155], v156 offset:2048
	ds_read_b128 v[156:159], v156 offset:3072
	ds_read_b128 v[160:163], v164
	ds_read_b128 v[178:181], v164 offset:1024
	ds_read_b128 v[182:185], v164 offset:2048
	ds_read_b128 v[186:189], v164 offset:3072
	v_lshl_add_u64 v[164:165], s[24:25], 0, v[136:137]
	s_add_i32 m0, s8, 0xc000
	ds_read_b128 v[190:193], v147
	ds_read_b128 v[194:197], v147 offset:1024
	ds_read_b128 v[198:201], v147 offset:2048
	ds_read_b128 v[202:205], v147 offset:3072
	ds_read_b128 v[206:209], v147 offset:4096
	ds_read_b128 v[210:213], v147 offset:5120
	ds_read_b128 v[214:217], v147 offset:6144
	ds_read_b128 v[218:221], v147 offset:7168
	global_load_lds_dwordx4 v[164:165], off
	v_lshl_add_u64 v[164:165], s[24:25], 0, v[138:139]
	s_add_i32 m0, s8, 0xe000
	s_nop 0
	global_load_lds_dwordx4 v[164:165], off
	s_waitcnt vmcnt(8)
	s_waitcnt lgkmcnt(0)
	s_barrier
	s_setprio 1
	s_waitcnt lgkmcnt(0)
	v_mfma_f32_16x16x32_bf16 v[126:129], v[140:143], v[190:193], v[126:129]
	v_mfma_f32_16x16x32_bf16 v[122:125], v[152:155], v[190:193], v[122:125]
	v_mfma_f32_16x16x32_bf16 v[118:121], v[140:143], v[198:201], v[118:121]
	v_mfma_f32_16x16x32_bf16 v[110:113], v[152:155], v[198:201], v[110:113]
	v_mfma_f32_16x16x32_bf16 v[102:105], v[140:143], v[206:209], v[102:105]
	v_mfma_f32_16x16x32_bf16 v[94:97], v[152:155], v[206:209], v[94:97]
	v_mfma_f32_16x16x32_bf16 v[86:89], v[140:143], v[214:217], v[86:89]
	v_mfma_f32_16x16x32_bf16 v[78:81], v[152:155], v[214:217], v[78:81]
	v_mfma_f32_16x16x32_bf16 v[126:129], v[148:151], v[194:197], v[126:129]
	v_mfma_f32_16x16x32_bf16 v[122:125], v[156:159], v[194:197], v[122:125]
	v_mfma_f32_16x16x32_bf16 v[118:121], v[148:151], v[202:205], v[118:121]
	v_mfma_f32_16x16x32_bf16 v[110:113], v[156:159], v[202:205], v[110:113]
	v_mfma_f32_16x16x32_bf16 v[102:105], v[148:151], v[210:213], v[102:105]
	v_mfma_f32_16x16x32_bf16 v[94:97], v[156:159], v[210:213], v[94:97]
	v_mfma_f32_16x16x32_bf16 v[86:89], v[148:151], v[218:221], v[86:89]
	v_mfma_f32_16x16x32_bf16 v[78:81], v[156:159], v[218:221], v[78:81]
	v_mfma_f32_16x16x32_bf16 v[114:117], v[160:163], v[190:193], v[114:117]
	v_mfma_f32_16x16x32_bf16 v[106:109], v[182:185], v[190:193], v[106:109]
	v_mfma_f32_16x16x32_bf16 v[98:101], v[160:163], v[198:201], v[98:101]
	v_mfma_f32_16x16x32_bf16 v[90:93], v[182:185], v[198:201], v[90:93]
	v_mfma_f32_16x16x32_bf16 v[82:85], v[160:163], v[206:209], v[82:85]
	v_mfma_f32_16x16x32_bf16 v[74:77], v[182:185], v[206:209], v[74:77]
	v_mfma_f32_16x16x32_bf16 v[70:73], v[160:163], v[214:217], v[70:73]
	v_mfma_f32_16x16x32_bf16 v[66:69], v[182:185], v[214:217], v[66:69]
	v_mfma_f32_16x16x32_bf16 v[114:117], v[178:181], v[194:197], v[114:117]
	v_mfma_f32_16x16x32_bf16 v[106:109], v[186:189], v[194:197], v[106:109]
	v_mfma_f32_16x16x32_bf16 v[98:101], v[178:181], v[202:205], v[98:101]
	v_mfma_f32_16x16x32_bf16 v[90:93], v[186:189], v[202:205], v[90:93]
	v_mfma_f32_16x16x32_bf16 v[82:85], v[178:181], v[210:213], v[82:85]
	v_mfma_f32_16x16x32_bf16 v[74:77], v[186:189], v[210:213], v[74:77]
	v_mfma_f32_16x16x32_bf16 v[70:73], v[178:181], v[218:221], v[70:73]
	v_mfma_f32_16x16x32_bf16 v[66:69], v[186:189], v[218:221], v[66:69]
	s_setprio 0
	s_barrier
	s_add_i32 s40, s40, s3
	v_lshl_add_u64 v[164:165], s[26:27], 0, v[0:1]
	s_mov_b32 m0, s40
	ds_read_b128 v[190:193], v147 offset:16384
	ds_read_b128 v[194:197], v147 offset:17408
	ds_read_b128 v[198:201], v147 offset:18432
	ds_read_b128 v[202:205], v147 offset:19456
	ds_read_b128 v[206:209], v147 offset:20480
	ds_read_b128 v[210:213], v147 offset:21504
	ds_read_b128 v[214:217], v147 offset:22528
	ds_read_b128 v[218:221], v147 offset:23552
	global_load_lds_dwordx4 v[164:165], off
	s_add_i32 m0, s40, 0x2000
	s_add_u32 s40, s26, 0x40000
	v_lshl_add_u64 v[166:167], s[26:27], 0, v[130:131]
	s_addc_u32 s41, s27, 0
	s_add_i32 s42, s42, s3
	global_load_lds_dwordx4 v[166:167], off
	v_lshl_add_u64 v[168:169], s[40:41], 0, v[0:1]
	s_mov_b32 m0, s42
	v_lshl_add_u64 v[170:171], s[28:29], 0, v[132:133]
	global_load_lds_dwordx4 v[168:169], off
	v_lshl_add_u64 v[168:169], s[40:41], 0, v[130:131]
	s_add_i32 m0, s42, 0x2000
	s_nop 0
	global_load_lds_dwordx4 v[168:169], off
	v_lshl_add_u64 v[168:169], s[28:29], 0, v[134:135]
	s_mov_b32 m0, s8
	s_nop 0
	global_load_lds_dwordx4 v[168:169], off
	s_mov_b32 m0, s9
	s_nop 0
	global_load_lds_dwordx4 v[170:171], off
	s_waitcnt vmcnt(8)
	s_waitcnt lgkmcnt(0)
	s_barrier
; #define PG8_STAGE(bufoff, gbase, voff) do { _Pragma("unroll") for (int _i = 0; _i < 2; ++_i) \
;         __builtin_amdgcn_global_load_lds((const unsigned*)((const char*)(gbase) + (voff)[_i]), (PG8_LAS unsigned*)(lds + (bufoff) + ldsw + _i * 8192), 16, 0, 0); } while (0)
; #define PG8_LDA(dst, b, h) do { _Pragma("unroll") for (int m = 0; m < 4; ++m) _Pragma("unroll") for (int k = 0; k < 2; ++k) dst[m][k] = *(const PG8_LAS bf16x8*)(lds + PG8_SA(b, h) + aoff + m * 2048 + k * 1024); } while (0)
; #define PG8_LDB(dst, b, h) do { _Pragma("unroll") for (int n = 0; n < 2; ++n) _Pragma("unroll") for (int k = 0; k < 2; ++k) dst[n][k] = *(const PG8_LAS bf16x8*)(lds + PG8_SB(b, h) + boff + n * 2048 + k * 1024); } while (0)
; #define PG8_MMA(ai, bj, At, Bt) do { __builtin_amdgcn_s_setprio(1); _Pragma("unroll") for (int m = 0; m < 4; ++m) _Pragma("unroll") for (int n = 0; n < 2; ++n) _Pragma("unroll") for (int k = 0; k < 2; ++k) \
;         acc[ai][bj][m][n] = __builtin_amdgcn_mfma_f32_16x16x32_bf16(Bt[n][k], At[m][k], acc[ai][bj][m][n], 0, 0, 0); __builtin_amdgcn_s_setprio(0); } while (0)
; #define PG8_WAIT_V(n) asm volatile("s_waitcnt vmcnt(" #n ")" ::: "memory")
; #define PG8_WAIT_L(n) asm volatile("s_waitcnt lgkmcnt(" #n ")" ::: "memory")
; #define PG8_BAR __builtin_amdgcn_s_barrier()
; #define PG8_SCHED __builtin_amdgcn_sched_barrier(0)
; template <class Epi, class Sched, bool ALIGN_EPI = false, bool SP2 = false, bool UNIFORM_NT = false>
; __device__ __forceinline__ void gemm_phase(PG8_LAS unsigned char* lds, const Gemm g, const Sched& S, const Epi& E, int tid_in) {
;     ...
;             PG8_WAIT_V(8); PG8_WAIT_L(0); PG8_BAR; PG8_MMA(1, 0, At, B0); PG8_MMA(1, 1, At, B1); PG8_BAR; PG8_SCHED;
;             PG8_LDB(B0, 1, 0); PG8_LDB(B1, 1, 1); PG8_SCHED; PG8_LDA(At, 1, 0); PG8_STAGE(PG8_SA(0, 1), a2 + hstepA, voffA);
;             PG8_WAIT_V(8); PG8_WAIT_L(0); PG8_BAR; PG8_MMA(0, 0, At, B0); PG8_MMA(0, 1, At, B1); PG8_BAR; PG8_SCHED;
	s_setprio 1
	s_waitcnt lgkmcnt(0)
	v_mfma_f32_16x16x32_bf16 v[62:65], v[140:143], v[190:193], v[62:65]
	v_mfma_f32_16x16x32_bf16 v[58:61], v[152:155], v[190:193], v[58:61]
	v_mfma_f32_16x16x32_bf16 v[54:57], v[140:143], v[198:201], v[54:57]
	v_mfma_f32_16x16x32_bf16 v[46:49], v[152:155], v[198:201], v[46:49]
	v_mfma_f32_16x16x32_bf16 v[38:41], v[140:143], v[206:209], v[38:41]
	v_mfma_f32_16x16x32_bf16 v[30:33], v[152:155], v[206:209], v[30:33]
	v_mfma_f32_16x16x32_bf16 v[22:25], v[140:143], v[214:217], v[22:25]
	v_mfma_f32_16x16x32_bf16 v[14:17], v[152:155], v[214:217], v[14:17]
	v_mfma_f32_16x16x32_bf16 v[62:65], v[148:151], v[194:197], v[62:65]
	v_mfma_f32_16x16x32_bf16 v[58:61], v[156:159], v[194:197], v[58:61]
	v_mfma_f32_16x16x32_bf16 v[54:57], v[148:151], v[202:205], v[54:57]
	v_mfma_f32_16x16x32_bf16 v[46:49], v[156:159], v[202:205], v[46:49]
	v_mfma_f32_16x16x32_bf16 v[38:41], v[148:151], v[210:213], v[38:41]
	v_mfma_f32_16x16x32_bf16 v[30:33], v[156:159], v[210:213], v[30:33]
	v_mfma_f32_16x16x32_bf16 v[22:25], v[148:151], v[218:221], v[22:25]
	v_mfma_f32_16x16x32_bf16 v[14:17], v[156:159], v[218:221], v[14:17]
	v_mfma_f32_16x16x32_bf16 v[50:53], v[160:163], v[190:193], v[50:53]
	v_mfma_f32_16x16x32_bf16 v[42:45], v[182:185], v[190:193], v[42:45]
	v_mfma_f32_16x16x32_bf16 v[34:37], v[160:163], v[198:201], v[34:37]
	v_mfma_f32_16x16x32_bf16 v[26:29], v[182:185], v[198:201], v[26:29]
	v_mfma_f32_16x16x32_bf16 v[18:21], v[160:163], v[206:209], v[18:21]
	v_mfma_f32_16x16x32_bf16 v[10:13], v[182:185], v[206:209], v[10:13]
	v_mfma_f32_16x16x32_bf16 v[6:9], v[160:163], v[214:217], v[6:9]
	v_mfma_f32_16x16x32_bf16 v[2:5], v[182:185], v[214:217], v[2:5]
	v_mfma_f32_16x16x32_bf16 v[50:53], v[178:181], v[194:197], v[50:53]
	v_mfma_f32_16x16x32_bf16 v[42:45], v[186:189], v[194:197], v[42:45]
	v_mfma_f32_16x16x32_bf16 v[34:37], v[178:181], v[202:205], v[34:37]
	v_mfma_f32_16x16x32_bf16 v[26:29], v[186:189], v[202:205], v[26:29]
	v_mfma_f32_16x16x32_bf16 v[18:21], v[178:181], v[210:213], v[18:21]
	v_mfma_f32_16x16x32_bf16 v[10:13], v[186:189], v[210:213], v[10:13]
	v_mfma_f32_16x16x32_bf16 v[6:9], v[178:181], v[218:221], v[6:9]
	v_mfma_f32_16x16x32_bf16 v[2:5], v[186:189], v[218:221], v[2:5]
	s_setprio 0
	s_barrier
	s_add_i32 s40, 0, 0x18000
	s_add_i32 s41, 0, 0x1c000
	v_add_u32_e32 v156, s40, v145
	v_add_u32_e32 v172, s41, v145
	ds_read_b128 v[140:143], v156
	ds_read_b128 v[148:151], v156 offset:1024
	ds_read_b128 v[152:155], v156 offset:2048
	ds_read_b128 v[156:159], v156 offset:3072
	ds_read_b128 v[160:163], v172
	ds_read_b128 v[178:181], v172 offset:1024
	ds_read_b128 v[182:185], v172 offset:2048
	ds_read_b128 v[186:189], v172 offset:3072
	s_add_u32 s28, s28, 0x40000
	s_addc_u32 s29, s29, 0
	s_mov_b32 m0, s14
	v_lshl_add_u64 v[172:173], s[28:29], 0, v[134:135]
	ds_read_b128 v[190:193], v147 offset:32768
	ds_read_b128 v[194:197], v147 offset:33792
	ds_read_b128 v[198:201], v147 offset:34816
	ds_read_b128 v[202:205], v147 offset:35840
	ds_read_b128 v[206:209], v147 offset:36864
	ds_read_b128 v[210:213], v147 offset:37888
	ds_read_b128 v[214:217], v147 offset:38912
	ds_read_b128 v[218:221], v147 offset:39936
	global_load_lds_dwordx4 v[172:173], off
	v_lshl_add_u64 v[172:173], s[28:29], 0, v[132:133]
	s_mov_b32 m0, s15
	s_nop 0
	global_load_lds_dwordx4 v[172:173], off
	s_waitcnt vmcnt(8)
	s_waitcnt lgkmcnt(0)
	s_barrier
	s_setprio 1
	s_waitcnt lgkmcnt(0)
	v_mfma_f32_16x16x32_bf16 v[126:129], v[140:143], v[190:193], v[126:129]
	v_mfma_f32_16x16x32_bf16 v[122:125], v[152:155], v[190:193], v[122:125]
	v_mfma_f32_16x16x32_bf16 v[118:121], v[140:143], v[198:201], v[118:121]
	v_mfma_f32_16x16x32_bf16 v[110:113], v[152:155], v[198:201], v[110:113]
	v_mfma_f32_16x16x32_bf16 v[102:105], v[140:143], v[206:209], v[102:105]
	v_mfma_f32_16x16x32_bf16 v[94:97], v[152:155], v[206:209], v[94:97]
	v_mfma_f32_16x16x32_bf16 v[86:89], v[140:143], v[214:217], v[86:89]
	v_mfma_f32_16x16x32_bf16 v[78:81], v[152:155], v[214:217], v[78:81]
	v_mfma_f32_16x16x32_bf16 v[126:129], v[148:151], v[194:197], v[126:129]
	v_mfma_f32_16x16x32_bf16 v[122:125], v[156:159], v[194:197], v[122:125]
	v_mfma_f32_16x16x32_bf16 v[118:121], v[148:151], v[202:205], v[118:121]
	v_mfma_f32_16x16x32_bf16 v[110:113], v[156:159], v[202:205], v[110:113]
	v_mfma_f32_16x16x32_bf16 v[102:105], v[148:151], v[210:213], v[102:105]
	v_mfma_f32_16x16x32_bf16 v[94:97], v[156:159], v[210:213], v[94:97]
	v_mfma_f32_16x16x32_bf16 v[86:89], v[148:151], v[218:221], v[86:89]
	v_mfma_f32_16x16x32_bf16 v[78:81], v[156:159], v[218:221], v[78:81]
	v_mfma_f32_16x16x32_bf16 v[114:117], v[160:163], v[190:193], v[114:117]
	v_mfma_f32_16x16x32_bf16 v[106:109], v[182:185], v[190:193], v[106:109]
	v_mfma_f32_16x16x32_bf16 v[98:101], v[160:163], v[198:201], v[98:101]
	v_mfma_f32_16x16x32_bf16 v[90:93], v[182:185], v[198:201], v[90:93]
	v_mfma_f32_16x16x32_bf16 v[82:85], v[160:163], v[206:209], v[82:85]
	v_mfma_f32_16x16x32_bf16 v[74:77], v[182:185], v[206:209], v[74:77]
	v_mfma_f32_16x16x32_bf16 v[70:73], v[160:163], v[214:217], v[70:73]
	v_mfma_f32_16x16x32_bf16 v[66:69], v[182:185], v[214:217], v[66:69]
	v_mfma_f32_16x16x32_bf16 v[114:117], v[178:181], v[194:197], v[114:117]
	v_mfma_f32_16x16x32_bf16 v[106:109], v[186:189], v[194:197], v[106:109]
	v_mfma_f32_16x16x32_bf16 v[98:101], v[178:181], v[202:205], v[98:101]
	v_mfma_f32_16x16x32_bf16 v[90:93], v[186:189], v[202:205], v[90:93]
	v_mfma_f32_16x16x32_bf16 v[82:85], v[178:181], v[210:213], v[82:85]
	v_mfma_f32_16x16x32_bf16 v[74:77], v[186:189], v[210:213], v[74:77]
	v_mfma_f32_16x16x32_bf16 v[70:73], v[178:181], v[218:221], v[70:73]
	v_mfma_f32_16x16x32_bf16 v[66:69], v[186:189], v[218:221], v[66:69]
	s_setprio 0
	s_barrier
; #define PG8_STAGE(bufoff, gbase, voff) do { _Pragma("unroll") for (int _i = 0; _i < 2; ++_i) \
;         __builtin_amdgcn_global_load_lds((const unsigned*)((const char*)(gbase) + (voff)[_i]), (PG8_LAS unsigned*)(lds + (bufoff) + ldsw + _i * 8192), 16, 0, 0); } while (0)
; #define PG8_LDA(dst, b, h) do { _Pragma("unroll") for (int m = 0; m < 4; ++m) _Pragma("unroll") for (int k = 0; k < 2; ++k) dst[m][k] = *(const PG8_LAS bf16x8*)(lds + PG8_SA(b, h) + aoff + m * 2048 + k * 1024); } while (0)
; #define PG8_MMA(ai, bj, At, Bt) do { __builtin_amdgcn_s_setprio(1); _Pragma("unroll") for (int m = 0; m < 4; ++m) _Pragma("unroll") for (int n = 0; n < 2; ++n) _Pragma("unroll") for (int k = 0; k < 2; ++k) \
;         acc[ai][bj][m][n] = __builtin_amdgcn_mfma_f32_16x16x32_bf16(Bt[n][k], At[m][k], acc[ai][bj][m][n], 0, 0, 0); __builtin_amdgcn_s_setprio(0); } while (0)
; #define PG8_WAIT_V(n) asm volatile("s_waitcnt vmcnt(" #n ")" ::: "memory")
; #define PG8_WAIT_L(n) asm volatile("s_waitcnt lgkmcnt(" #n ")" ::: "memory")
; #define PG8_BAR __builtin_amdgcn_s_barrier()
; #define PG8_SCHED __builtin_amdgcn_sched_barrier(0)
; template <class Epi, class Sched, bool ALIGN_EPI = false, bool SP2 = false, bool UNIFORM_NT = false>
; __device__ __forceinline__ void gemm_phase(PG8_LAS unsigned char* lds, const Gemm g, const Sched& S, const Epi& E, int tid_in) {
;     ...
;             PG8_LDA(At, 1, 1); PG8_STAGE(PG8_SB(1, 0), b3, voffB); PG8_STAGE(PG8_SB(1, 1), b3 + hstepB, voffB); PG8_STAGE(PG8_SA(1, 0), a3, voffA);
;             PG8_WAIT_V(8); PG8_WAIT_L(0); PG8_BAR; PG8_MMA(1, 0, At, B0); PG8_MMA(1, 1, At, B1); PG8_BAR; PG8_SCHED;
	s_add_i32 s28, s40, s3
	v_lshl_add_u64 v[164:165], v[164:165], 0, s[82:83]
	s_mov_b32 m0, s28
	ds_read_b128 v[190:193], v147 offset:49152
	ds_read_b128 v[194:197], v147 offset:50176
	ds_read_b128 v[198:201], v147 offset:51200
	ds_read_b128 v[202:205], v147 offset:52224
	ds_read_b128 v[206:209], v147 offset:53248
	ds_read_b128 v[210:213], v147 offset:54272
	ds_read_b128 v[214:217], v147 offset:55296
	ds_read_b128 v[218:221], v147 offset:56320
	global_load_lds_dwordx4 v[164:165], off
	s_add_i32 m0, s28, 0x2000
	s_add_u32 s26, s26, 0x40080
	v_lshl_add_u64 v[164:165], v[166:167], 0, s[82:83]
	s_addc_u32 s27, s27, 0
	s_add_i32 s28, s41, s3
	global_load_lds_dwordx4 v[164:165], off
	v_lshl_add_u64 v[164:165], s[26:27], 0, v[0:1]
	s_mov_b32 m0, s28
	s_nop 0
	global_load_lds_dwordx4 v[164:165], off
	v_lshl_add_u64 v[164:165], s[26:27], 0, v[130:131]
	s_add_i32 m0, s28, 0x2000
	s_nop 0
	global_load_lds_dwordx4 v[164:165], off
	v_lshl_add_u64 v[164:165], v[168:169], 0, s[82:83]
	s_mov_b32 m0, s30
	s_nop 0
	global_load_lds_dwordx4 v[164:165], off
	v_lshl_add_u64 v[164:165], v[170:171], 0, s[82:83]
	s_mov_b32 m0, s31
	s_nop 0
	global_load_lds_dwordx4 v[164:165], off
	s_waitcnt vmcnt(8)
	s_waitcnt lgkmcnt(0)
	s_barrier
	s_setprio 1
	s_waitcnt lgkmcnt(0)
	v_mfma_f32_16x16x32_bf16 v[62:65], v[140:143], v[190:193], v[62:65]
	v_mfma_f32_16x16x32_bf16 v[58:61], v[152:155], v[190:193], v[58:61]
	v_mfma_f32_16x16x32_bf16 v[54:57], v[140:143], v[198:201], v[54:57]
	v_mfma_f32_16x16x32_bf16 v[46:49], v[152:155], v[198:201], v[46:49]
	v_mfma_f32_16x16x32_bf16 v[38:41], v[140:143], v[206:209], v[38:41]
	v_mfma_f32_16x16x32_bf16 v[30:33], v[152:155], v[206:209], v[30:33]
	v_mfma_f32_16x16x32_bf16 v[22:25], v[140:143], v[214:217], v[22:25]
	v_mfma_f32_16x16x32_bf16 v[14:17], v[152:155], v[214:217], v[14:17]
	v_mfma_f32_16x16x32_bf16 v[62:65], v[148:151], v[194:197], v[62:65]
	v_mfma_f32_16x16x32_bf16 v[58:61], v[156:159], v[194:197], v[58:61]
	v_mfma_f32_16x16x32_bf16 v[54:57], v[148:151], v[202:205], v[54:57]
	v_mfma_f32_16x16x32_bf16 v[46:49], v[156:159], v[202:205], v[46:49]
	v_mfma_f32_16x16x32_bf16 v[38:41], v[148:151], v[210:213], v[38:41]
	v_mfma_f32_16x16x32_bf16 v[30:33], v[156:159], v[210:213], v[30:33]
	v_mfma_f32_16x16x32_bf16 v[22:25], v[148:151], v[218:221], v[22:25]
	v_mfma_f32_16x16x32_bf16 v[14:17], v[156:159], v[218:221], v[14:17]
	v_mfma_f32_16x16x32_bf16 v[50:53], v[160:163], v[190:193], v[50:53]
	v_mfma_f32_16x16x32_bf16 v[42:45], v[182:185], v[190:193], v[42:45]
	v_mfma_f32_16x16x32_bf16 v[34:37], v[160:163], v[198:201], v[34:37]
	v_mfma_f32_16x16x32_bf16 v[26:29], v[182:185], v[198:201], v[26:29]
	v_mfma_f32_16x16x32_bf16 v[18:21], v[160:163], v[206:209], v[18:21]
	v_mfma_f32_16x16x32_bf16 v[10:13], v[182:185], v[206:209], v[10:13]
	v_mfma_f32_16x16x32_bf16 v[6:9], v[160:163], v[214:217], v[6:9]
	v_mfma_f32_16x16x32_bf16 v[2:5], v[182:185], v[214:217], v[2:5]
	v_mfma_f32_16x16x32_bf16 v[50:53], v[178:181], v[194:197], v[50:53]
	v_mfma_f32_16x16x32_bf16 v[42:45], v[186:189], v[194:197], v[42:45]
	v_mfma_f32_16x16x32_bf16 v[34:37], v[178:181], v[202:205], v[34:37]
	v_mfma_f32_16x16x32_bf16 v[26:29], v[186:189], v[202:205], v[26:29]
	v_mfma_f32_16x16x32_bf16 v[18:21], v[178:181], v[210:213], v[18:21]
	v_mfma_f32_16x16x32_bf16 v[10:13], v[186:189], v[210:213], v[10:13]
	v_mfma_f32_16x16x32_bf16 v[6:9], v[178:181], v[218:221], v[6:9]
	v_mfma_f32_16x16x32_bf16 v[2:5], v[186:189], v[218:221], v[2:5]
	s_setprio 0
	s_barrier
	s_add_i32 s37, s37, 2
	s_add_u32 s24, s24, 0x100
	s_addc_u32 s25, s25, 0
	s_add_u32 s35, s35, 0x100
	s_addc_u32 s36, s36, 0
	s_cmp_gt_u32 s37, 13
	s_cbranch_scc0 .LBB0_833
	s_and_b64 vcc, exec, s[4:5]
	s_cbranch_vccz .LBB0_836
	s_barrier
